# grid barrier: census words cached in LDS instead of two dependent system-scope loads per barrier (on top of strip+sbtrim)
# speedup vs baseline: 1.0148x; 1.0010x over previous
; __device__ __forceinline__ unsigned xb_ld(unsigned* p)              { return __hip_atomic_load(p, __ATOMIC_RELAXED, __HIP_MEMORY_SCOPE_AGENT); }
; __device__ __forceinline__ unsigned xb_add(unsigned* p, unsigned v) { return __hip_atomic_fetch_add(p, v, __ATOMIC_RELAXED, __HIP_MEMORY_SCOPE_AGENT); }
; #define XB_SPIN(cond, bar) do { unsigned _sp = 0; while (cond) { __builtin_amdgcn_s_sleep(1); \
;     if ((++_sp & 255u) == 0u) { if (xb_ld(&(bar)[XB_TMO])) break; if (_sp > XB_SPIN_CAP) { atomicAdd(&(bar)[XB_TMO], 1u); break; } } } } while (0)
; __device__ __forceinline__ void xcd_barrier(const XcdBarrier& b) {
;     ...
;         unsigned nloc = b.st[0], nx = b.st[1];
;         if (nloc == 0u) { xcd_barrier_complete(bar, b.x, nloc, nx); b.st[0] = nloc; b.st[1] = nx; }
;         const unsigned old = xb_add(&bar[XB_XSUB(b.x)], 1u);
;         const unsigned gen = old / nloc;
;         if (old + 1u == (gen + 1u) * nloc) {
;             __builtin_amdgcn_fence(__ATOMIC_RELEASE, "agent");
;             asm volatile("s_waitcnt vmcnt(0)" ::: "memory");
;             const unsigned og = xb_add(&bar[XB_TOP], 1u);
;             const unsigned tg = og / nx;
;             if (og + 1u == (tg + 1u) * nx) xb_add(&bar[XB_TOPGEN], 1u);
;             else XB_SPIN(xb_ld(&bar[XB_TOPGEN]) == tg, bar);
;             __builtin_amdgcn_fence(__ATOMIC_ACQUIRE, "agent");
;             xb_add(&bar[XB_XGEN(b.x)], 1u);
;             asm volatile("s_waitcnt vmcnt(0)" ::: "memory");
;         } else {
;             XB_SPIN(xb_ld(&bar[XB_XGEN(b.x)]) == gen, bar);
.LBB0_66:
	s_or_b64 exec, exec, s[4:5]
	v_mov_b32_e32 v1, 0x25100
	ds_write_b32 v1, v2
	ds_write_b32 v1, v0 offset:4
	s_lshl_b32 s4, s25, 8
	s_add_u32 s4, s66, s4
	s_addc_u32 s5, s67, 0
	v_mov_b32_e32 v1, 0x1000
	v_mov_b32_e32 v3, 1
	global_atomic_add v1, v1, v3, s[4:5] offset:1024 sc0
	v_cvt_f32_u32_e32 v3, v2
	v_sub_u32_e32 v4, 0, v2
	v_rcp_iflag_f32_e32 v3, v3
	s_nop 0
	v_mul_f32_e32 v3, 0x4f7ffffe, v3
	v_cvt_u32_f32_e32 v3, v3
	v_mul_lo_u32 v4, v4, v3
	v_mul_hi_u32 v4, v3, v4
	v_add_u32_e32 v3, v3, v4
	s_waitcnt vmcnt(0)
	v_mul_hi_u32 v3, v1, v3
	v_mul_lo_u32 v5, v3, v2
	v_add_u32_e32 v4, 1, v1
	v_sub_u32_e32 v1, v1, v5
	v_add_u32_e32 v6, 1, v3
	v_cmp_ge_u32_e32 vcc, v1, v2
	v_sub_u32_e32 v5, v1, v2
	s_nop 0
	v_cndmask_b32_e32 v3, v3, v6, vcc
	v_cndmask_b32_e32 v1, v1, v5, vcc
	v_add_u32_e32 v5, 1, v3
	v_cmp_ge_u32_e32 vcc, v1, v2
	s_nop 1
	v_cndmask_b32_e32 v1, v3, v5, vcc
	v_mad_u64_u32 v[2:3], s[6:7], v2, v1, v[2:3]
	v_cmp_ne_u32_e32 vcc, v4, v2
	s_and_saveexec_b64 s[6:7], vcc
	s_xor_b64 s[6:7], exec, s[6:7]
	s_cbranch_execz .LBB0_80
	v_mov_b32_e32 v0, 0x2000
	global_load_dword v0, v0, s[4:5] offset:1024 sc1
	s_add_u32 s10, s4, 0x2400
	s_addc_u32 s11, s5, 0
	s_waitcnt vmcnt(0)
	v_cmp_eq_u32_e32 vcc, v0, v1
	s_and_saveexec_b64 s[8:9], vcc
	s_cbranch_execz .LBB0_79
	s_mov_b32 s22, 1
	s_mov_b64 s[12:13], 0
	v_mov_b32_e32 v0, 0
	s_branch .LBB0_70

; __device__ __forceinline__ void xcd_barrier(const XcdBarrier& b) {
;     asm volatile("s_waitcnt vmcnt(0)" ::: "memory");
;     __syncthreads();
;     if (mk_tid() == 0) {
;         unsigned* bar = b.bar;
;         __builtin_amdgcn_s_waitcnt(0);
;         unsigned nloc = b.st[0], nx = b.st[1];
;         if (nloc == 0u) { xcd_barrier_complete(bar, b.x, nloc, nx); b.st[0] = nloc; b.st[1] = nx; }
.LBB0_340:
	v_readlane_b32 s8, v253, 0
	v_readlane_b32 s9, v253, 1
	s_or_b64 s[6:7], s[8:9], s[6:7]
	s_and_b64 vcc, exec, s[6:7]
	s_cbranch_vccnz .LBB0_390
	s_waitcnt vmcnt(0)
	s_waitcnt vmcnt(0) lgkmcnt(0)
	s_barrier
	s_getreg_b32 s5, hwreg(HW_REG_HW_ID, 0, 6)
	s_and_b32 s5, s5, 63
	s_lshl_b32 s5, s5, 2
	s_or_b32 s5, s5, 0x25000
	v_mov_b32_e32 v1, s5
	ds_read_b32 v1, v1
	v_mbcnt_lo_u32_b32 v2, -1, 0
	v_mbcnt_hi_u32_b32 v2, -1, v2
	s_waitcnt lgkmcnt(0)
	v_readfirstlane_b32 s5, v1
	s_lshl_b32 s5, s5, 6
	v_sub_u32_e32 v1, 0, v2
	v_cmp_eq_u32_e32 vcc, s5, v1
	s_and_saveexec_b64 s[6:7], vcc
	s_cbranch_execz .LBB0_389
	v_readlane_b32 s8, v253, 2
	v_readlane_b32 s9, v253, 3
	s_waitcnt vmcnt(0) expcnt(0) lgkmcnt(0)
	s_nop 0
	v_mov_b64_e32 v[2:3], s[8:9]
	v_mov_b32_e32 v4, 0x25100
	ds_read_b32 v2, v4 offset:4
	ds_read_b32 v4, v4
	s_waitcnt vmcnt(0) lgkmcnt(0)
	v_cmp_eq_u32_e32 vcc, 0, v4
	s_and_saveexec_b64 s[8:9], vcc
	s_cbranch_execz .LBB0_357
	s_mov_b32 s5, 1
	s_branch .LBB0_345

; __device__ __forceinline__ void xcd_barrier(const XcdBarrier& b) {
;     asm volatile("s_waitcnt vmcnt(0)" ::: "memory");
;     __syncthreads();
;     if (mk_tid() == 0) {
;         unsigned* bar = b.bar;
;         __builtin_amdgcn_s_waitcnt(0);
;         unsigned nloc = b.st[0], nx = b.st[1];
;         if (nloc == 0u) { xcd_barrier_complete(bar, b.x, nloc, nx); b.st[0] = nloc; b.st[1] = nx; }
.LBB0_644:
	v_readlane_b32 s6, v253, 0
	v_readlane_b32 s8, v255, 33
	v_readlane_b32 s7, v253, 1
	v_readlane_b32 s9, v255, 34
	s_or_b64 s[6:7], s[6:7], s[8:9]
	s_and_b64 vcc, exec, s[6:7]
	s_cbranch_vccnz .LBB0_694
	s_waitcnt vmcnt(0)
	s_waitcnt vmcnt(0) lgkmcnt(0)
	s_barrier
	s_getreg_b32 s5, hwreg(HW_REG_HW_ID, 0, 6)
	s_and_b32 s5, s5, 63
	s_lshl_b32 s5, s5, 2
	s_or_b32 s5, s5, 0x25000
	v_mov_b32_e32 v1, s5
	ds_read_b32 v1, v1
	v_mbcnt_lo_u32_b32 v2, -1, 0
	v_mbcnt_hi_u32_b32 v2, -1, v2
	s_waitcnt lgkmcnt(0)
	v_readfirstlane_b32 s5, v1
	s_lshl_b32 s5, s5, 6
	v_sub_u32_e32 v1, 0, v2
	v_cmp_eq_u32_e32 vcc, s5, v1
	s_and_saveexec_b64 s[6:7], vcc
	s_cbranch_execz .LBB0_693
	v_readlane_b32 s8, v253, 2
	v_readlane_b32 s9, v253, 3
	s_waitcnt vmcnt(0) expcnt(0) lgkmcnt(0)
	s_nop 0
	v_mov_b64_e32 v[2:3], s[8:9]
	v_mov_b32_e32 v4, 0x25100
	ds_read_b32 v2, v4 offset:4
	ds_read_b32 v4, v4
	s_waitcnt vmcnt(0) lgkmcnt(0)
	v_cmp_eq_u32_e32 vcc, 0, v4
	s_and_saveexec_b64 s[8:9], vcc
	s_cbranch_execz .LBB0_661
	s_mov_b32 s5, 1
	s_branch .LBB0_649

; __device__ __forceinline__ void xcd_barrier(const XcdBarrier& b) {
;     asm volatile("s_waitcnt vmcnt(0)" ::: "memory");
;     __syncthreads();
;     if (mk_tid() == 0) {
;         unsigned* bar = b.bar;
;         __builtin_amdgcn_s_waitcnt(0);
;         unsigned nloc = b.st[0], nx = b.st[1];
;         if (nloc == 0u) { xcd_barrier_complete(bar, b.x, nloc, nx); b.st[0] = nloc; b.st[1] = nx; }
.LBB0_1159:
	v_readlane_b32 s4, v255, 27
	v_readlane_b32 s5, v255, 28
	s_and_b64 s[4:5], s[4:5], s[6:7]
	s_and_b64 s[4:5], s[14:15], s[4:5]
	v_readlane_b32 s6, v253, 0
	s_xor_b64 s[4:5], s[4:5], -1
	v_readlane_b32 s7, v253, 1
	s_or_b64 s[4:5], s[6:7], s[4:5]
	s_and_b64 vcc, exec, s[4:5]
	s_cbranch_vccnz .LBB0_102
	s_waitcnt vmcnt(0)
	s_waitcnt vmcnt(0) lgkmcnt(0)
	s_barrier
	s_getreg_b32 s4, hwreg(HW_REG_HW_ID, 0, 6)
	s_and_b32 s4, s4, 63
	s_lshl_b32 s4, s4, 2
	s_or_b32 s4, s4, 0x25000
	v_mov_b32_e32 v1, s4
	ds_read_b32 v1, v1
	v_mbcnt_lo_u32_b32 v2, -1, 0
	v_mbcnt_hi_u32_b32 v2, -1, v2
	s_waitcnt lgkmcnt(0)
	v_readfirstlane_b32 s4, v1
	s_lshl_b32 s4, s4, 6
	v_sub_u32_e32 v1, 0, v2
	v_cmp_eq_u32_e32 vcc, s4, v1
	s_and_saveexec_b64 s[6:7], vcc
	s_cbranch_execz .LBB0_101
	v_readlane_b32 s4, v253, 2
	v_readlane_b32 s5, v253, 3
	s_waitcnt vmcnt(0) expcnt(0) lgkmcnt(0)
	s_nop 0
	v_mov_b64_e32 v[2:3], s[4:5]
	v_mov_b32_e32 v4, 0x25100
	ds_read_b32 v2, v4 offset:4
	ds_read_b32 v4, v4
	s_waitcnt vmcnt(0) lgkmcnt(0)
	v_cmp_eq_u32_e32 vcc, 0, v4
	s_and_saveexec_b64 s[8:9], vcc
	s_cbranch_execz .LBB0_1176
	s_mov_b32 s4, 1
	s_branch .LBB0_1164

; __device__ __forceinline__ void xcd_barrier(const XcdBarrier& b) {
;     asm volatile("s_waitcnt vmcnt(0)" ::: "memory");
;     __syncthreads();
;     if (mk_tid() == 0) {
;         unsigned* bar = b.bar;
;         __builtin_amdgcn_s_waitcnt(0);
;         unsigned nloc = b.st[0], nx = b.st[1];
;         if (nloc == 0u) { xcd_barrier_complete(bar, b.x, nloc, nx); b.st[0] = nloc; b.st[1] = nx; }
; __global__ void __launch_bounds__(NT) fwd_megakernel(Params P) {
;     ...
;     if (RUN(NPHASE - 1)) { if (RUN(NPHASE - 2)) xcd_barrier(bar); p_ln<true>(Y2, nullptr, P.out, P.ln_ffn_g + (DEPTH - 1) * DM, P.ln_ffn_b + (DEPTH - 1) * DM, (const float*)ST2); }
.LBB0_1207:
	s_cmp_lt_i32 s68, 17
	s_cselect_b64 s[0:1], -1, 0
	s_cmp_gt_i32 s69, 16
	s_cselect_b64 s[4:5], -1, 0
	s_and_b64 s[0:1], s[0:1], s[4:5]
	s_and_b64 vcc, exec, s[0:1]
	s_cbranch_vccz .LBB0_1261
	s_cmp_gt_i32 s68, 15
	s_cbranch_scc1 .LBB0_1258
	s_waitcnt vmcnt(0)
	s_waitcnt vmcnt(0) lgkmcnt(0)
	s_barrier
	s_getreg_b32 s0, hwreg(HW_REG_HW_ID, 0, 6)
	s_and_b32 s0, s0, 63
	s_lshl_b32 s0, s0, 2
	s_or_b32 s0, s0, 0x25000
	v_mov_b32_e32 v0, s0
	ds_read_b32 v0, v0
	v_mbcnt_lo_u32_b32 v1, -1, 0
	v_mbcnt_hi_u32_b32 v1, -1, v1
	s_waitcnt lgkmcnt(0)
	v_readfirstlane_b32 s0, v0
	s_lshl_b32 s0, s0, 6
	v_sub_u32_e32 v0, 0, v1
	v_cmp_eq_u32_e32 vcc, s0, v0
	s_and_saveexec_b64 s[0:1], vcc
	s_cbranch_execz .LBB0_1257
	v_readlane_b32 s4, v253, 2
	v_readlane_b32 s5, v253, 3
	s_waitcnt vmcnt(0) expcnt(0) lgkmcnt(0)
	s_nop 0
	v_mov_b64_e32 v[0:1], s[4:5]
	v_mov_b32_e32 v2, 0x25100
	ds_read_b32 v0, v2 offset:4
	ds_read_b32 v2, v2
	s_waitcnt vmcnt(0) lgkmcnt(0)
	v_cmp_eq_u32_e32 vcc, 0, v2
	s_and_saveexec_b64 s[4:5], vcc
	s_cbranch_execz .LBB0_1225
	s_mov_b32 s3, 1
	v_mov_b32_e32 v16, 0
	s_branch .LBB0_1213
